# v18 + pooling phase main loop: all 16 row loads issued before the first wait (was 6, wait, 10)
# speedup vs baseline: 1.0065x; 1.0065x over previous
.LBB0_158:
	v_add_co_u32_e32 v4, vcc, s36, v142
	v_lshl_add_u32 v132, s23, 9, v182
	s_nop 0
	v_addc_co_u32_e32 v5, vcc, -1, v143, vcc
	v_add_co_u32_e32 v8, vcc, s37, v142
	global_load_dwordx4 v[64:67], v[4:5], off offset:-4096
	s_nop 0
	global_load_dwordx4 v[4:7], v[4:5], off
	v_addc_co_u32_e32 v9, vcc, -1, v143, vcc
	v_add_co_u32_e32 v16, vcc, s38, v142
	global_load_dwordx4 v[12:15], v[8:9], off offset:-4096
	s_nop 0
	global_load_dwordx4 v[8:11], v[8:9], off
	v_addc_co_u32_e32 v17, vcc, -1, v143, vcc
	global_load_dwordx4 v[20:23], v[16:17], off offset:-4096
	s_nop 0
	global_load_dwordx4 v[16:19], v[16:17], off
	v_add_co_u32_e32 v24, vcc, s39, v142
	s_nop 1
	v_addc_co_u32_e32 v25, vcc, -1, v143, vcc
	v_add_co_u32_e32 v32, vcc, s40, v142
	s_nop 1
	v_addc_co_u32_e32 v33, vcc, -1, v143, vcc
	v_add_co_u32_e32 v40, vcc, s41, v142
	s_nop 1
	v_addc_co_u32_e32 v41, vcc, -1, v143, vcc
	v_add_co_u32_e32 v52, vcc, s42, v142
	s_nop 1
	v_addc_co_u32_e32 v53, vcc, -1, v143, vcc
	global_load_dwordx4 v[60:63], v[142:143], off offset:-4096
	global_load_dwordx4 v[56:59], v[142:143], off
	global_load_dwordx4 v[28:31], v[24:25], off offset:-4096
	s_nop 0
	global_load_dwordx4 v[24:27], v[24:25], off
	s_nop 0
	global_load_dwordx4 v[36:39], v[32:33], off offset:-4096
	s_nop 0
	global_load_dwordx4 v[32:35], v[32:33], off
	s_nop 0
	global_load_dwordx4 v[44:47], v[40:41], off offset:-4096
	s_nop 0
	global_load_dwordx4 v[40:43], v[40:41], off
	s_nop 0
	global_load_dwordx4 v[48:51], v[52:53], off offset:-4096
	s_nop 0
	global_load_dwordx4 v[52:55], v[52:53], off
	s_waitcnt vmcnt(15)
	v_mov_b32_e32 v148, v65
	s_waitcnt vmcnt(14)
	v_mov_b32_e32 v149, v5
	v_mov_b32_e32 v152, v67
	v_mov_b32_e32 v153, v7
	s_waitcnt vmcnt(13)
	v_mov_b32_e32 v156, v13
	s_waitcnt vmcnt(12)
	v_mov_b32_e32 v157, v9
	v_mov_b32_e32 v160, v15
	v_mov_b32_e32 v161, v11
	v_mov_b32_e32 v146, v64
	v_mov_b32_e32 v147, v4
	v_mov_b32_e32 v150, v66
	v_mov_b32_e32 v151, v6
	v_mov_b32_e32 v154, v12
	v_mov_b32_e32 v155, v8
	v_mov_b32_e32 v158, v14
	v_mov_b32_e32 v159, v10
	s_waitcnt vmcnt(11)
	v_mov_b32_e32 v164, v21
	s_waitcnt vmcnt(10)
	v_mov_b32_e32 v165, v17
	v_mov_b32_e32 v168, v23
	v_mov_b32_e32 v169, v19
	v_pk_mul_f32 v[148:149], v[148:149], v[148:149]
	v_pk_mul_f32 v[152:153], v[152:153], v[152:153]
	v_pk_mul_f32 v[156:157], v[156:157], v[156:157]
	v_pk_mul_f32 v[160:161], v[160:161], v[160:161]
	v_mov_b32_e32 v162, v20
	v_mov_b32_e32 v163, v16
	v_mov_b32_e32 v166, v22
	v_mov_b32_e32 v167, v18
	v_pk_mul_f32 v[164:165], v[164:165], v[164:165]
	v_pk_mul_f32 v[168:169], v[168:169], v[168:169]
	v_pk_fma_f32 v[146:147], v[146:147], v[146:147], v[148:149]
	v_pk_fma_f32 v[148:149], v[150:151], v[150:151], v[152:153]
	v_pk_fma_f32 v[150:151], v[154:155], v[154:155], v[156:157]
	v_pk_fma_f32 v[152:153], v[158:159], v[158:159], v[160:161]
	v_pk_fma_f32 v[154:155], v[162:163], v[162:163], v[164:165]
	v_pk_fma_f32 v[156:157], v[166:167], v[166:167], v[168:169]
	v_pk_add_f32 v[150:151], v[150:151], v[152:153]
	v_pk_add_f32 v[152:153], v[154:155], v[156:157]
	ds_bpermute_b32 v154, v129, v150
	ds_bpermute_b32 v155, v129, v151
	ds_bpermute_b32 v156, v129, v152
	ds_bpermute_b32 v157, v129, v153
	v_pk_add_f32 v[146:147], v[146:147], v[148:149]
	ds_bpermute_b32 v148, v129, v146
	s_waitcnt lgkmcnt(3)
	v_pk_add_f32 v[150:151], v[150:151], v[154:155]
	ds_bpermute_b32 v154, v184, v150
	ds_bpermute_b32 v155, v184, v151
	s_waitcnt lgkmcnt(3)
	v_pk_add_f32 v[152:153], v[152:153], v[156:157]
	ds_bpermute_b32 v156, v184, v152
	ds_bpermute_b32 v157, v184, v153
	ds_bpermute_b32 v149, v129, v147
	s_waitcnt lgkmcnt(3)
	v_pk_add_f32 v[150:151], v[150:151], v[154:155]
	ds_bpermute_b32 v154, v185, v150
	ds_bpermute_b32 v155, v185, v151
	s_waitcnt lgkmcnt(3)
	v_pk_add_f32 v[152:153], v[152:153], v[156:157]
	s_waitcnt lgkmcnt(2)
	v_pk_add_f32 v[146:147], v[146:147], v[148:149]
	ds_bpermute_b32 v148, v184, v146
	ds_bpermute_b32 v149, v184, v147
	s_waitcnt lgkmcnt(2)
	v_pk_add_f32 v[150:151], v[150:151], v[154:155]
	ds_bpermute_b32 v154, v186, v150
	ds_bpermute_b32 v155, v186, v151
	s_waitcnt lgkmcnt(2)
	v_pk_add_f32 v[146:147], v[146:147], v[148:149]
	ds_bpermute_b32 v148, v185, v146
	ds_bpermute_b32 v149, v185, v147
	s_waitcnt lgkmcnt(2)
	v_pk_add_f32 v[150:151], v[150:151], v[154:155]
	ds_bpermute_b32 v154, v185, v152
	ds_bpermute_b32 v155, v185, v153
	s_waitcnt lgkmcnt(2)
	v_pk_add_f32 v[146:147], v[146:147], v[148:149]
	ds_bpermute_b32 v148, v186, v146
	ds_bpermute_b32 v149, v186, v147
	s_waitcnt lgkmcnt(2)
	v_pk_add_f32 v[152:153], v[152:153], v[154:155]
	ds_bpermute_b32 v154, v186, v152
	ds_bpermute_b32 v155, v186, v153
	s_waitcnt vmcnt(9)
	v_mov_b32_e32 v174, v61
	s_waitcnt vmcnt(7)
	v_mov_b32_e32 v158, v29
	s_waitcnt vmcnt(6)
	v_mov_b32_e32 v159, v25
	v_mov_b32_e32 v156, v28
	v_mov_b32_e32 v157, v24
	s_waitcnt vmcnt(3)
	v_mov_b32_e32 v168, v45
	s_waitcnt vmcnt(2)
	v_mov_b32_e32 v169, v41
	v_mov_b32_e32 v166, v44
	v_mov_b32_e32 v167, v40
	v_pk_mul_f32 v[168:169], v[168:169], v[168:169]
	v_mov_b32_e32 v170, v47
	v_mov_b32_e32 v171, v43
	v_pk_fma_f32 v[166:167], v[166:167], v[166:167], v[168:169]
	v_mov_b32_e32 v168, v46
	v_mov_b32_e32 v169, v42
	v_pk_mul_f32 v[170:171], v[170:171], v[170:171]
	v_pk_mul_f32 v[158:159], v[158:159], v[158:159]
	v_pk_fma_f32 v[168:169], v[168:169], v[168:169], v[170:171]
	v_mov_b32_e32 v160, v31
	v_pk_add_f32 v[166:167], v[166:167], v[168:169]
	ds_bpermute_b32 v168, v129, v166
	ds_bpermute_b32 v169, v129, v167
	v_mov_b32_e32 v161, v27
	v_pk_fma_f32 v[156:157], v[156:157], v[156:157], v[158:159]
	v_mov_b32_e32 v158, v30
	v_mov_b32_e32 v159, v26
	v_pk_mul_f32 v[160:161], v[160:161], v[160:161]
	s_waitcnt lgkmcnt(0)
	v_pk_add_f32 v[166:167], v[166:167], v[168:169]
	v_pk_fma_f32 v[158:159], v[158:159], v[158:159], v[160:161]
	ds_bpermute_b32 v168, v184, v166
	ds_bpermute_b32 v169, v184, v167
	v_pk_add_f32 v[156:157], v[156:157], v[158:159]
	ds_bpermute_b32 v158, v129, v156
	ds_bpermute_b32 v159, v129, v157
	v_pk_add_f32 v[162:163], v[152:153], v[154:155]
	s_waitcnt lgkmcnt(2)
	v_pk_add_f32 v[166:167], v[166:167], v[168:169]
	ds_bpermute_b32 v168, v185, v166
	ds_bpermute_b32 v169, v185, v167
	s_waitcnt lgkmcnt(2)
	v_pk_add_f32 v[156:157], v[156:157], v[158:159]
	ds_bpermute_b32 v158, v184, v156
	ds_bpermute_b32 v159, v184, v157
	ds_bpermute_b32 v160, v187, v150
	s_waitcnt lgkmcnt(3)
	v_pk_add_f32 v[166:167], v[166:167], v[168:169]
	ds_bpermute_b32 v168, v186, v166
	ds_bpermute_b32 v169, v186, v167
	ds_bpermute_b32 v161, v187, v151
	ds_bpermute_b32 v164, v187, v162
	ds_bpermute_b32 v165, v187, v163
	s_waitcnt lgkmcnt(6)
	v_pk_add_f32 v[156:157], v[156:157], v[158:159]
	ds_bpermute_b32 v158, v185, v156
	ds_bpermute_b32 v159, v185, v157
	s_waitcnt vmcnt(1)
	v_mov_b32_e32 v170, v49
	s_waitcnt vmcnt(0)
	v_mov_b32_e32 v171, v53
	s_waitcnt lgkmcnt(5)
	v_pk_add_f32 v[166:167], v[166:167], v[168:169]
	v_mov_b32_e32 v168, v48
	v_mov_b32_e32 v169, v52
	v_pk_mul_f32 v[170:171], v[170:171], v[170:171]
	v_mov_b32_e32 v172, v51
	v_mov_b32_e32 v173, v55
	s_waitcnt lgkmcnt(4)
	v_pk_add_f32 v[152:153], v[150:151], v[160:161]
	s_waitcnt lgkmcnt(2)
	v_pk_add_f32 v[150:151], v[162:163], v[164:165]
	v_mov_b32_e32 v162, v37
	v_mov_b32_e32 v163, v33
	v_pk_fma_f32 v[168:169], v[168:169], v[168:169], v[170:171]
	v_mov_b32_e32 v170, v50
	v_mov_b32_e32 v171, v54
	v_pk_mul_f32 v[172:173], v[172:173], v[172:173]
	v_mov_b32_e32 v175, v57
	s_waitcnt lgkmcnt(0)
	v_pk_add_f32 v[158:159], v[156:157], v[158:159]
	v_mov_b32_e32 v156, v36
	v_mov_b32_e32 v157, v32
	v_pk_mul_f32 v[162:163], v[162:163], v[162:163]
	v_mov_b32_e32 v164, v39
	v_mov_b32_e32 v165, v35
	v_pk_fma_f32 v[170:171], v[170:171], v[170:171], v[172:173]
	v_mov_b32_e32 v172, v60
	v_mov_b32_e32 v173, v56
	v_pk_mul_f32 v[174:175], v[174:175], v[174:175]
	v_mov_b32_e32 v176, v63
	v_mov_b32_e32 v177, v59
	v_pk_fma_f32 v[156:157], v[156:157], v[156:157], v[162:163]
	v_mov_b32_e32 v162, v38
	v_mov_b32_e32 v163, v34
	v_pk_mul_f32 v[164:165], v[164:165], v[164:165]
	v_pk_fma_f32 v[172:173], v[172:173], v[172:173], v[174:175]
	v_mov_b32_e32 v174, v62
	v_mov_b32_e32 v175, v58
	v_pk_mul_f32 v[176:177], v[176:177], v[176:177]
	v_pk_fma_f32 v[162:163], v[162:163], v[162:163], v[164:165]
	v_pk_fma_f32 v[174:175], v[174:175], v[174:175], v[176:177]
	v_pk_add_f32 v[162:163], v[156:157], v[162:163]
	v_pk_add_f32 v[168:169], v[168:169], v[170:171]
	v_pk_add_f32 v[172:173], v[172:173], v[174:175]
	ds_bpermute_b32 v164, v129, v162
	ds_bpermute_b32 v165, v129, v163
	ds_bpermute_b32 v170, v129, v168
	ds_bpermute_b32 v171, v129, v169
	ds_bpermute_b32 v174, v129, v172
	ds_bpermute_b32 v175, v129, v173
	s_waitcnt lgkmcnt(4)
	v_pk_add_f32 v[162:163], v[162:163], v[164:165]
	ds_bpermute_b32 v160, v186, v158
	s_waitcnt lgkmcnt(3)
	v_pk_add_f32 v[168:169], v[168:169], v[170:171]
	ds_bpermute_b32 v161, v186, v159
	s_waitcnt lgkmcnt(2)
	v_pk_add_f32 v[172:173], v[172:173], v[174:175]
	ds_bpermute_b32 v164, v184, v162
	ds_bpermute_b32 v165, v184, v163
	ds_bpermute_b32 v170, v184, v168
	ds_bpermute_b32 v171, v184, v169
	ds_bpermute_b32 v174, v184, v172
	ds_bpermute_b32 v175, v184, v173
	s_waitcnt lgkmcnt(6)
	v_pk_add_f32 v[158:159], v[158:159], v[160:161]
	s_waitcnt lgkmcnt(4)
	v_pk_add_f32 v[162:163], v[162:163], v[164:165]
	s_waitcnt lgkmcnt(2)
	v_pk_add_f32 v[168:169], v[168:169], v[170:171]
	ds_bpermute_b32 v160, v187, v158
	s_waitcnt lgkmcnt(1)
	v_pk_add_f32 v[172:173], v[172:173], v[174:175]
	ds_bpermute_b32 v161, v187, v159
	ds_bpermute_b32 v164, v185, v162
	ds_bpermute_b32 v165, v185, v163
	ds_bpermute_b32 v170, v185, v168
	ds_bpermute_b32 v171, v185, v169
	ds_bpermute_b32 v174, v185, v172
	ds_bpermute_b32 v175, v185, v173
	ds_bpermute_b32 v176, v187, v166
	ds_bpermute_b32 v177, v187, v167
	s_waitcnt lgkmcnt(8)
	v_pk_add_f32 v[158:159], v[158:159], v[160:161]
	s_waitcnt lgkmcnt(6)
	v_pk_add_f32 v[160:161], v[162:163], v[164:165]
	s_waitcnt lgkmcnt(4)
	v_pk_add_f32 v[168:169], v[168:169], v[170:171]
	s_waitcnt lgkmcnt(2)
	v_pk_add_f32 v[174:175], v[172:173], v[174:175]
	ds_bpermute_b32 v162, v186, v160
	ds_bpermute_b32 v163, v186, v161
	s_waitcnt lgkmcnt(2)
	v_pk_add_f32 v[166:167], v[166:167], v[176:177]
	ds_bpermute_b32 v170, v186, v168
	ds_bpermute_b32 v171, v186, v169
	ds_bpermute_b32 v176, v186, v174
	ds_bpermute_b32 v177, v186, v175
	v_pk_add_f32 v[146:147], v[146:147], v[148:149]
	s_waitcnt lgkmcnt(4)
	v_pk_add_f32 v[160:161], v[160:161], v[162:163]
	s_waitcnt lgkmcnt(2)
	v_pk_add_f32 v[168:169], v[168:169], v[170:171]
	ds_bpermute_b32 v148, v187, v146
	s_waitcnt lgkmcnt(1)
	v_pk_add_f32 v[174:175], v[174:175], v[176:177]
	ds_bpermute_b32 v149, v187, v147
	ds_bpermute_b32 v162, v187, v160
	ds_bpermute_b32 v163, v187, v161
	ds_bpermute_b32 v170, v187, v168
	ds_bpermute_b32 v171, v187, v169
	ds_bpermute_b32 v176, v187, v174
	ds_bpermute_b32 v177, v187, v175
	s_waitcnt lgkmcnt(6)
	v_pk_add_f32 v[146:147], v[146:147], v[148:149]
	s_waitcnt lgkmcnt(4)
	v_pk_add_f32 v[160:161], v[160:161], v[162:163]
	s_waitcnt lgkmcnt(2)
	v_pk_add_f32 v[168:169], v[168:169], v[170:171]
	ds_bpermute_b32 v148, v188, v146
	s_waitcnt lgkmcnt(1)
	v_pk_add_f32 v[174:175], v[174:175], v[176:177]
	ds_bpermute_b32 v149, v188, v147
	ds_bpermute_b32 v154, v188, v152
	ds_bpermute_b32 v155, v188, v153
	ds_bpermute_b32 v156, v188, v150
	ds_bpermute_b32 v157, v188, v151
	ds_bpermute_b32 v164, v188, v158
	ds_bpermute_b32 v165, v188, v159
	ds_bpermute_b32 v162, v188, v160
	ds_bpermute_b32 v163, v188, v161
	ds_bpermute_b32 v172, v188, v166
	ds_bpermute_b32 v173, v188, v167
	ds_bpermute_b32 v170, v188, v168
	ds_bpermute_b32 v171, v188, v169
	ds_bpermute_b32 v176, v188, v174
	ds_bpermute_b32 v177, v188, v175
	s_and_saveexec_b64 s[4:5], s[8:9]
	s_cbranch_execz .LBB0_160
	v_add_u32_e32 v178, v132, v180
	s_waitcnt lgkmcnt(12)
	v_pk_add_f32 v[154:155], v[152:153], v[154:155]
	v_pk_add_f32 v[152:153], v[146:147], v[148:149]
	s_waitcnt lgkmcnt(8)
	v_pk_add_f32 v[148:149], v[158:159], v[164:165]
	v_pk_add_f32 v[146:147], v[150:151], v[156:157]
	ds_write_b128 v178, v[146:149] offset:16
	s_waitcnt lgkmcnt(5)
	v_pk_add_f32 v[148:149], v[166:167], v[172:173]
	v_pk_add_f32 v[146:147], v[160:161], v[162:163]
	ds_write_b128 v178, v[146:149] offset:32
	s_waitcnt lgkmcnt(2)
	v_pk_add_f32 v[148:149], v[174:175], v[176:177]
	v_pk_add_f32 v[146:147], v[168:169], v[170:171]
	ds_write_b128 v178, v[152:155]
	ds_write_b128 v178, v[146:149] offset:48
